# layer-1 MLP down-projection weight conversion deferred from the prologue to 48 otherwise idle workgroups in the PLE/KVQ deal; plus staggered GEMM order and DMA rebalance
# speedup vs baseline: 1.0045x; 1.0029x over previous
.LBB0_58:
	s_andn2_b64 vcc, exec, s[6:7]
	s_cbranch_vccnz .LBB0_62
	s_and_b64 vcc, exec, s[22:23]
	s_cbranch_vccnz .LBB0_62
	s_load_dwordx2 s[6:7], s[18:19], 0xd8
	s_add_i32 s13, s29, 0xe000
	s_and_b64 s[14:15], s[22:23], exec
	s_cselect_b32 s14, 0x4000000, 0
	v_mov_b32_e32 v33, v5
	s_waitcnt lgkmcnt(0)
	s_add_u32 s14, s6, s14
	s_addc_u32 s15, s7, 0
	s_lshl_b32 s6, s45, 5
	s_and_b32 s6, s6, 0x7e0
	s_and_b32 s7, s13, 0xffc0
	s_lshl_b32 s13, s6, 2
	s_add_u32 s14, s14, s13
	s_addc_u32 s15, s15, 0
	s_mov_b32 s12, 0
	v_lshl_add_u64 v[34:35], s[14:15], 0, v[32:33]
	s_mov_b32 s13, s7
	s_mov_b32 s14, 1
	s_mov_b32 s15, 32

.LBB0_1110:
	s_waitcnt vmcnt(0)
	s_add_i32 s0, s74, -16
	s_cmp_gt_u32 s0, 5
	s_barrier
	s_cbranch_scc0 .Ldw2_kvqs
	s_add_i32 s0, s74, 0xffffffea
	s_cmp_gt_u32 s0, 5
	s_cbranch_scc1 .LBB0_1389
.Ldw2_begin:
	s_load_dwordx2 s[26:27], s[86:87], 0xd8
	s_load_dwordx2 s[28:29], s[86:87], 0x118
	s_and_b32 s30, s2, 7
	s_lshl_b32 s31, s0, 3
	s_add_i32 s30, s30, s31
	s_lshl_b32 s30, s30, 3
	s_add_i32 s30, s30, s85
	v_lshrrev_b32_e32 v2, 3, v244
	v_and_b32_e32 v3, 7, v244
	v_lshlrev_b32_e32 v4, 13, v2
	v_lshl_add_u32 v4, v3, 4, v4
	s_lshl_b32 s31, s85, 14
	v_lshlrev_b32_e32 v5, 7, v2
	v_add_u32_e32 v5, s31, v5
	v_xor_b32_e32 v6, 0, v3
	v_lshl_add_u32 v110, v6, 4, v5
	v_xor_b32_e32 v6, 1, v3
	v_lshl_add_u32 v111, v6, 4, v5
	v_xor_b32_e32 v6, 2, v3
	v_lshl_add_u32 v112, v6, 4, v5
	v_xor_b32_e32 v6, 3, v3
	v_lshl_add_u32 v113, v6, 4, v5
	v_xor_b32_e32 v6, 4, v3
	v_lshl_add_u32 v114, v6, 4, v5
	v_xor_b32_e32 v6, 5, v3
	v_lshl_add_u32 v115, v6, 4, v5
	v_xor_b32_e32 v6, 6, v3
	v_lshl_add_u32 v116, v6, 4, v5
	v_xor_b32_e32 v6, 7, v3
	v_lshl_add_u32 v117, v6, 4, v5
	v_lshlrev_b32_e32 v7, 10, v3
	v_add_u32_e32 v7, s31, v7
	v_add_u32_e32 v8, 0, v2
	v_lshrrev_b32_e32 v9, 2, v8
	v_xor_b32_e32 v9, v9, v3
	v_and_b32_e32 v8, 3, v8
	v_lshl_add_u32 v8, v9, 2, v8
	v_lshl_add_u32 v118, v8, 2, v7
	v_add_u32_e32 v8, 8, v2
	v_lshrrev_b32_e32 v9, 2, v8
	v_xor_b32_e32 v9, v9, v3
	v_and_b32_e32 v8, 3, v8
	v_lshl_add_u32 v8, v9, 2, v8
	v_lshl_add_u32 v119, v8, 2, v7
	v_add_u32_e32 v8, 16, v2
	v_lshrrev_b32_e32 v9, 2, v8
	v_xor_b32_e32 v9, v9, v3
	v_and_b32_e32 v8, 3, v8
	v_lshl_add_u32 v8, v9, 2, v8
	v_lshl_add_u32 v120, v8, 2, v7
	v_add_u32_e32 v8, 24, v2
	v_lshrrev_b32_e32 v9, 2, v8
	v_xor_b32_e32 v9, v9, v3
	v_and_b32_e32 v8, 3, v8
	v_lshl_add_u32 v8, v9, 2, v8
	v_lshl_add_u32 v121, v8, 2, v7
	v_lshlrev_b32_e32 v74, 14, v2
	v_lshl_add_u32 v74, v3, 4, v74
	v_add_u32_e32 v75, 0x20000, v74
	v_add_u32_e32 v76, 0x40000, v74
	v_add_u32_e32 v77, 0x60000, v74
	s_waitcnt lgkmcnt(0)
	s_add_u32 s26, s26, 0x4000000
	s_addc_u32 s27, s27, 0
	s_add_u32 s28, s28, 0x8f00000
	s_addc_u32 s29, s29, 0
	s_lshr_b32 s34, s30, 6
	s_and_b32 s35, s30, 63
	s_mov_b32 s40, s30
	s_lshl_b32 s36, s34, 19
	s_lshl_b32 s37, s35, 7
	s_add_i32 s36, s36, s37
	s_add_u32 s38, s26, s36
	s_addc_u32 s39, s27, 0
	global_load_dwordx4 v[10:13], v4, s[38:39] nt
	s_add_u32 s38, s38, 0x10000
	s_addc_u32 s39, s39, 0
	global_load_dwordx4 v[14:17], v4, s[38:39] nt
	s_add_u32 s38, s38, 0x10000
	s_addc_u32 s39, s39, 0
	global_load_dwordx4 v[18:21], v4, s[38:39] nt
	s_add_u32 s38, s38, 0x10000
	s_addc_u32 s39, s39, 0
	global_load_dwordx4 v[22:25], v4, s[38:39] nt
	s_add_u32 s38, s38, 0x10000
	s_addc_u32 s39, s39, 0
	global_load_dwordx4 v[26:29], v4, s[38:39] nt
	s_add_u32 s38, s38, 0x10000
	s_addc_u32 s39, s39, 0
	global_load_dwordx4 v[30:33], v4, s[38:39] nt
	s_add_u32 s38, s38, 0x10000
	s_addc_u32 s39, s39, 0
	global_load_dwordx4 v[34:37], v4, s[38:39] nt
	s_add_u32 s38, s38, 0x10000
	s_addc_u32 s39, s39, 0
	global_load_dwordx4 v[38:41], v4, s[38:39] nt
	s_addk_i32 s30, 0x180
	s_and_b32 s30, s30, 0x1fff
	s_lshr_b32 s34, s30, 6
	s_and_b32 s35, s30, 63
	s_mov_b32 s41, s30
	s_lshl_b32 s36, s34, 19
	s_lshl_b32 s37, s35, 7
	s_add_i32 s36, s36, s37
	s_add_u32 s38, s26, s36
	s_addc_u32 s39, s27, 0
	global_load_dwordx4 v[42:45], v4, s[38:39] nt
	s_add_u32 s38, s38, 0x10000
	s_addc_u32 s39, s39, 0
	global_load_dwordx4 v[46:49], v4, s[38:39] nt
	s_add_u32 s38, s38, 0x10000
	s_addc_u32 s39, s39, 0
	global_load_dwordx4 v[50:53], v4, s[38:39] nt
	s_add_u32 s38, s38, 0x10000
	s_addc_u32 s39, s39, 0
	global_load_dwordx4 v[54:57], v4, s[38:39] nt
	s_add_u32 s38, s38, 0x10000
	s_addc_u32 s39, s39, 0
	global_load_dwordx4 v[58:61], v4, s[38:39] nt
	s_add_u32 s38, s38, 0x10000
	s_addc_u32 s39, s39, 0
	global_load_dwordx4 v[62:65], v4, s[38:39] nt
	s_add_u32 s38, s38, 0x10000
	s_addc_u32 s39, s39, 0
	global_load_dwordx4 v[66:69], v4, s[38:39] nt
	s_add_u32 s38, s38, 0x10000
	s_addc_u32 s39, s39, 0
	global_load_dwordx4 v[70:73], v4, s[38:39] nt
	s_addk_i32 s30, 0x180
	s_and_b32 s30, s30, 0x1fff
	s_waitcnt vmcnt(8)
	ds_write_b128 v110, v[10:13]
	ds_write_b128 v111, v[14:17] offset:1024
	ds_write_b128 v112, v[18:21] offset:2048
	ds_write_b128 v113, v[22:25] offset:3072
	ds_write_b128 v114, v[26:29] offset:4096
	ds_write_b128 v115, v[30:33] offset:5120
	ds_write_b128 v116, v[34:37] offset:6144
	ds_write_b128 v117, v[38:41] offset:7168
	ds_read2_b32 v[10:11], v118 offset1:32
	ds_read2_b32 v[12:13], v118 offset0:64 offset1:96
	ds_read2_b32 v[14:15], v118 offset0:128 offset1:160
	ds_read2_b32 v[16:17], v118 offset0:192 offset1:224
	ds_read2_b32 v[18:19], v119 offset1:32
	ds_read2_b32 v[20:21], v119 offset0:64 offset1:96
	ds_read2_b32 v[22:23], v119 offset0:128 offset1:160
	ds_read2_b32 v[24:25], v119 offset0:192 offset1:224
	ds_read2_b32 v[26:27], v120 offset1:32
	ds_read2_b32 v[28:29], v120 offset0:64 offset1:96
	ds_read2_b32 v[30:31], v120 offset0:128 offset1:160
	ds_read2_b32 v[32:33], v120 offset0:192 offset1:224
	ds_read2_b32 v[34:35], v121 offset1:32
	ds_read2_b32 v[36:37], v121 offset0:64 offset1:96
	ds_read2_b32 v[38:39], v121 offset0:128 offset1:160
	ds_read2_b32 v[40:41], v121 offset0:192 offset1:224
	s_lshr_b32 s34, s40, 6
	s_and_b32 s35, s40, 63
	s_lshl_b32 s36, s35, 19
	s_lshl_b32 s37, s34, 7
	s_add_i32 s36, s36, s37
	s_add_u32 s38, s28, s36
	s_addc_u32 s39, s29, 0
	s_waitcnt lgkmcnt(12)
	v_cvt_pk_bf16_f32 v78, v10, v11
	v_cvt_pk_bf16_f32 v79, v12, v13
	v_cvt_pk_bf16_f32 v80, v14, v15
	v_cvt_pk_bf16_f32 v81, v16, v17
	s_waitcnt lgkmcnt(8)
	v_cvt_pk_bf16_f32 v82, v18, v19
	v_cvt_pk_bf16_f32 v83, v20, v21
	v_cvt_pk_bf16_f32 v84, v22, v23
	v_cvt_pk_bf16_f32 v85, v24, v25
	s_waitcnt lgkmcnt(4)
	v_cvt_pk_bf16_f32 v86, v26, v27
	v_cvt_pk_bf16_f32 v87, v28, v29
	v_cvt_pk_bf16_f32 v88, v30, v31
	v_cvt_pk_bf16_f32 v89, v32, v33
	s_waitcnt lgkmcnt(0)
	v_cvt_pk_bf16_f32 v90, v34, v35
	v_cvt_pk_bf16_f32 v91, v36, v37
	v_cvt_pk_bf16_f32 v92, v38, v39
	v_cvt_pk_bf16_f32 v93, v40, v41
	global_store_dwordx4 v74, v[78:81], s[38:39]
	global_store_dwordx4 v75, v[82:85], s[38:39]
	global_store_dwordx4 v76, v[86:89], s[38:39]
	global_store_dwordx4 v77, v[90:93], s[38:39]
	s_lshr_b32 s34, s30, 6
	s_and_b32 s35, s30, 63
	s_mov_b32 s40, s30
	s_lshl_b32 s36, s34, 19
	s_lshl_b32 s37, s35, 7
	s_add_i32 s36, s36, s37
	s_add_u32 s38, s26, s36
	s_addc_u32 s39, s27, 0
	global_load_dwordx4 v[10:13], v4, s[38:39] nt
	s_add_u32 s38, s38, 0x10000
	s_addc_u32 s39, s39, 0
	global_load_dwordx4 v[14:17], v4, s[38:39] nt
	s_add_u32 s38, s38, 0x10000
	s_addc_u32 s39, s39, 0
	global_load_dwordx4 v[18:21], v4, s[38:39] nt
	s_add_u32 s38, s38, 0x10000
	s_addc_u32 s39, s39, 0
	global_load_dwordx4 v[22:25], v4, s[38:39] nt
	s_add_u32 s38, s38, 0x10000
	s_addc_u32 s39, s39, 0
	global_load_dwordx4 v[26:29], v4, s[38:39] nt
	s_add_u32 s38, s38, 0x10000
	s_addc_u32 s39, s39, 0
	global_load_dwordx4 v[30:33], v4, s[38:39] nt
	s_add_u32 s38, s38, 0x10000
	s_addc_u32 s39, s39, 0
	global_load_dwordx4 v[34:37], v4, s[38:39] nt
	s_add_u32 s38, s38, 0x10000
	s_addc_u32 s39, s39, 0
	global_load_dwordx4 v[38:41], v4, s[38:39] nt
	s_addk_i32 s30, 0x180
	s_and_b32 s30, s30, 0x1fff
	s_mov_b32 s42, 10
.Ldw2_loop:
	s_waitcnt vmcnt(12)
	ds_write_b128 v110, v[42:45]
	ds_write_b128 v111, v[46:49] offset:1024
	ds_write_b128 v112, v[50:53] offset:2048
	ds_write_b128 v113, v[54:57] offset:3072
	ds_write_b128 v114, v[58:61] offset:4096
	ds_write_b128 v115, v[62:65] offset:5120
	ds_write_b128 v116, v[66:69] offset:6144
	ds_write_b128 v117, v[70:73] offset:7168
	ds_read2_b32 v[42:43], v118 offset1:32
	ds_read2_b32 v[44:45], v118 offset0:64 offset1:96
	ds_read2_b32 v[46:47], v118 offset0:128 offset1:160
	ds_read2_b32 v[48:49], v118 offset0:192 offset1:224
	ds_read2_b32 v[50:51], v119 offset1:32
	ds_read2_b32 v[52:53], v119 offset0:64 offset1:96
	ds_read2_b32 v[54:55], v119 offset0:128 offset1:160
	ds_read2_b32 v[56:57], v119 offset0:192 offset1:224
	ds_read2_b32 v[58:59], v120 offset1:32
	ds_read2_b32 v[60:61], v120 offset0:64 offset1:96
	ds_read2_b32 v[62:63], v120 offset0:128 offset1:160
	ds_read2_b32 v[64:65], v120 offset0:192 offset1:224
	ds_read2_b32 v[66:67], v121 offset1:32
	ds_read2_b32 v[68:69], v121 offset0:64 offset1:96
	ds_read2_b32 v[70:71], v121 offset0:128 offset1:160
	ds_read2_b32 v[72:73], v121 offset0:192 offset1:224
	s_lshr_b32 s34, s41, 6
	s_and_b32 s35, s41, 63
	s_lshl_b32 s36, s35, 19
	s_lshl_b32 s37, s34, 7
	s_add_i32 s36, s36, s37
	s_add_u32 s38, s28, s36
	s_addc_u32 s39, s29, 0
	s_waitcnt lgkmcnt(12)
	v_cvt_pk_bf16_f32 v94, v42, v43
	v_cvt_pk_bf16_f32 v95, v44, v45
	v_cvt_pk_bf16_f32 v96, v46, v47
	v_cvt_pk_bf16_f32 v97, v48, v49
	s_waitcnt lgkmcnt(8)
	v_cvt_pk_bf16_f32 v98, v50, v51
	v_cvt_pk_bf16_f32 v99, v52, v53
	v_cvt_pk_bf16_f32 v100, v54, v55
	v_cvt_pk_bf16_f32 v101, v56, v57
	s_waitcnt lgkmcnt(4)
	v_cvt_pk_bf16_f32 v102, v58, v59
	v_cvt_pk_bf16_f32 v103, v60, v61
	v_cvt_pk_bf16_f32 v104, v62, v63
	v_cvt_pk_bf16_f32 v105, v64, v65
	s_waitcnt lgkmcnt(0)
	v_cvt_pk_bf16_f32 v106, v66, v67
	v_cvt_pk_bf16_f32 v107, v68, v69
	v_cvt_pk_bf16_f32 v108, v70, v71
	v_cvt_pk_bf16_f32 v109, v72, v73
	global_store_dwordx4 v74, v[94:97], s[38:39]
	global_store_dwordx4 v75, v[98:101], s[38:39]
	global_store_dwordx4 v76, v[102:105], s[38:39]
	global_store_dwordx4 v77, v[106:109], s[38:39]
	s_lshr_b32 s34, s30, 6
	s_and_b32 s35, s30, 63
	s_mov_b32 s41, s30
	s_lshl_b32 s36, s34, 19
	s_lshl_b32 s37, s35, 7
	s_add_i32 s36, s36, s37
	s_add_u32 s38, s26, s36
	s_addc_u32 s39, s27, 0
	global_load_dwordx4 v[42:45], v4, s[38:39] nt
	s_add_u32 s38, s38, 0x10000
	s_addc_u32 s39, s39, 0
	global_load_dwordx4 v[46:49], v4, s[38:39] nt
	s_add_u32 s38, s38, 0x10000
	s_addc_u32 s39, s39, 0
	global_load_dwordx4 v[50:53], v4, s[38:39] nt
	s_add_u32 s38, s38, 0x10000
	s_addc_u32 s39, s39, 0
	global_load_dwordx4 v[54:57], v4, s[38:39] nt
	s_add_u32 s38, s38, 0x10000
	s_addc_u32 s39, s39, 0
	global_load_dwordx4 v[58:61], v4, s[38:39] nt
	s_add_u32 s38, s38, 0x10000
	s_addc_u32 s39, s39, 0
	global_load_dwordx4 v[62:65], v4, s[38:39] nt
	s_add_u32 s38, s38, 0x10000
	s_addc_u32 s39, s39, 0
	global_load_dwordx4 v[66:69], v4, s[38:39] nt
	s_add_u32 s38, s38, 0x10000
	s_addc_u32 s39, s39, 0
	global_load_dwordx4 v[70:73], v4, s[38:39] nt
	s_addk_i32 s30, 0x180
	s_and_b32 s30, s30, 0x1fff
	s_waitcnt vmcnt(12)
	ds_write_b128 v110, v[10:13]
	ds_write_b128 v111, v[14:17] offset:1024
	ds_write_b128 v112, v[18:21] offset:2048
	ds_write_b128 v113, v[22:25] offset:3072
	ds_write_b128 v114, v[26:29] offset:4096
	ds_write_b128 v115, v[30:33] offset:5120
	ds_write_b128 v116, v[34:37] offset:6144
	ds_write_b128 v117, v[38:41] offset:7168
	ds_read2_b32 v[10:11], v118 offset1:32
	ds_read2_b32 v[12:13], v118 offset0:64 offset1:96
	ds_read2_b32 v[14:15], v118 offset0:128 offset1:160
	ds_read2_b32 v[16:17], v118 offset0:192 offset1:224
	ds_read2_b32 v[18:19], v119 offset1:32
	ds_read2_b32 v[20:21], v119 offset0:64 offset1:96
	ds_read2_b32 v[22:23], v119 offset0:128 offset1:160
	ds_read2_b32 v[24:25], v119 offset0:192 offset1:224
	ds_read2_b32 v[26:27], v120 offset1:32
	ds_read2_b32 v[28:29], v120 offset0:64 offset1:96
	ds_read2_b32 v[30:31], v120 offset0:128 offset1:160
	ds_read2_b32 v[32:33], v120 offset0:192 offset1:224
	ds_read2_b32 v[34:35], v121 offset1:32
	ds_read2_b32 v[36:37], v121 offset0:64 offset1:96
	ds_read2_b32 v[38:39], v121 offset0:128 offset1:160
	ds_read2_b32 v[40:41], v121 offset0:192 offset1:224
	s_lshr_b32 s34, s40, 6
	s_and_b32 s35, s40, 63
	s_lshl_b32 s36, s35, 19
	s_lshl_b32 s37, s34, 7
	s_add_i32 s36, s36, s37
	s_add_u32 s38, s28, s36
	s_addc_u32 s39, s29, 0
	s_waitcnt lgkmcnt(12)
	v_cvt_pk_bf16_f32 v78, v10, v11
	v_cvt_pk_bf16_f32 v79, v12, v13
	v_cvt_pk_bf16_f32 v80, v14, v15
	v_cvt_pk_bf16_f32 v81, v16, v17
	s_waitcnt lgkmcnt(8)
	v_cvt_pk_bf16_f32 v82, v18, v19
	v_cvt_pk_bf16_f32 v83, v20, v21
	v_cvt_pk_bf16_f32 v84, v22, v23
	v_cvt_pk_bf16_f32 v85, v24, v25
	s_waitcnt lgkmcnt(4)
	v_cvt_pk_bf16_f32 v86, v26, v27
	v_cvt_pk_bf16_f32 v87, v28, v29
	v_cvt_pk_bf16_f32 v88, v30, v31
	v_cvt_pk_bf16_f32 v89, v32, v33
	s_waitcnt lgkmcnt(0)
	v_cvt_pk_bf16_f32 v90, v34, v35
	v_cvt_pk_bf16_f32 v91, v36, v37
	v_cvt_pk_bf16_f32 v92, v38, v39
	v_cvt_pk_bf16_f32 v93, v40, v41
	global_store_dwordx4 v74, v[78:81], s[38:39]
	global_store_dwordx4 v75, v[82:85], s[38:39]
	global_store_dwordx4 v76, v[86:89], s[38:39]
	global_store_dwordx4 v77, v[90:93], s[38:39]
	s_lshr_b32 s34, s30, 6
	s_and_b32 s35, s30, 63
	s_mov_b32 s40, s30
	s_lshl_b32 s36, s34, 19
	s_lshl_b32 s37, s35, 7
	s_add_i32 s36, s36, s37
	s_add_u32 s38, s26, s36
	s_addc_u32 s39, s27, 0
	global_load_dwordx4 v[10:13], v4, s[38:39] nt
	s_add_u32 s38, s38, 0x10000
	s_addc_u32 s39, s39, 0
	global_load_dwordx4 v[14:17], v4, s[38:39] nt
	s_add_u32 s38, s38, 0x10000
	s_addc_u32 s39, s39, 0
	global_load_dwordx4 v[18:21], v4, s[38:39] nt
	s_add_u32 s38, s38, 0x10000
	s_addc_u32 s39, s39, 0
	global_load_dwordx4 v[22:25], v4, s[38:39] nt
	s_add_u32 s38, s38, 0x10000
	s_addc_u32 s39, s39, 0
	global_load_dwordx4 v[26:29], v4, s[38:39] nt
	s_add_u32 s38, s38, 0x10000
	s_addc_u32 s39, s39, 0
	global_load_dwordx4 v[30:33], v4, s[38:39] nt
	s_add_u32 s38, s38, 0x10000
	s_addc_u32 s39, s39, 0
	global_load_dwordx4 v[34:37], v4, s[38:39] nt
	s_add_u32 s38, s38, 0x10000
	s_addc_u32 s39, s39, 0
	global_load_dwordx4 v[38:41], v4, s[38:39] nt
	s_addk_i32 s30, 0x180
	s_and_b32 s30, s30, 0x1fff
	s_add_i32 s42, s42, -1
	s_cmp_lg_u32 s42, 0
	s_cbranch_scc1 .Ldw2_loop
	s_waitcnt vmcnt(12)
	ds_write_b128 v110, v[42:45]
	ds_write_b128 v111, v[46:49] offset:1024
	ds_write_b128 v112, v[50:53] offset:2048
	ds_write_b128 v113, v[54:57] offset:3072
	ds_write_b128 v114, v[58:61] offset:4096
	ds_write_b128 v115, v[62:65] offset:5120
	ds_write_b128 v116, v[66:69] offset:6144
	ds_write_b128 v117, v[70:73] offset:7168
	ds_read2_b32 v[42:43], v118 offset1:32
	ds_read2_b32 v[44:45], v118 offset0:64 offset1:96
	ds_read2_b32 v[46:47], v118 offset0:128 offset1:160
	ds_read2_b32 v[48:49], v118 offset0:192 offset1:224
	ds_read2_b32 v[50:51], v119 offset1:32
	ds_read2_b32 v[52:53], v119 offset0:64 offset1:96
	ds_read2_b32 v[54:55], v119 offset0:128 offset1:160
	ds_read2_b32 v[56:57], v119 offset0:192 offset1:224
	ds_read2_b32 v[58:59], v120 offset1:32
	ds_read2_b32 v[60:61], v120 offset0:64 offset1:96
	ds_read2_b32 v[62:63], v120 offset0:128 offset1:160
	ds_read2_b32 v[64:65], v120 offset0:192 offset1:224
	ds_read2_b32 v[66:67], v121 offset1:32
	ds_read2_b32 v[68:69], v121 offset0:64 offset1:96
	ds_read2_b32 v[70:71], v121 offset0:128 offset1:160
	ds_read2_b32 v[72:73], v121 offset0:192 offset1:224
	s_lshr_b32 s34, s41, 6
	s_and_b32 s35, s41, 63
	s_lshl_b32 s36, s35, 19
	s_lshl_b32 s37, s34, 7
	s_add_i32 s36, s36, s37
	s_add_u32 s38, s28, s36
	s_addc_u32 s39, s29, 0
	s_waitcnt lgkmcnt(12)
	v_cvt_pk_bf16_f32 v94, v42, v43
	v_cvt_pk_bf16_f32 v95, v44, v45
	v_cvt_pk_bf16_f32 v96, v46, v47
	v_cvt_pk_bf16_f32 v97, v48, v49
	s_waitcnt lgkmcnt(8)
	v_cvt_pk_bf16_f32 v98, v50, v51
	v_cvt_pk_bf16_f32 v99, v52, v53
	v_cvt_pk_bf16_f32 v100, v54, v55
	v_cvt_pk_bf16_f32 v101, v56, v57
	s_waitcnt lgkmcnt(4)
	v_cvt_pk_bf16_f32 v102, v58, v59
	v_cvt_pk_bf16_f32 v103, v60, v61
	v_cvt_pk_bf16_f32 v104, v62, v63
	v_cvt_pk_bf16_f32 v105, v64, v65
	s_waitcnt lgkmcnt(0)
	v_cvt_pk_bf16_f32 v106, v66, v67
	v_cvt_pk_bf16_f32 v107, v68, v69
	v_cvt_pk_bf16_f32 v108, v70, v71
	v_cvt_pk_bf16_f32 v109, v72, v73
	global_store_dwordx4 v74, v[94:97], s[38:39]
	global_store_dwordx4 v75, v[98:101], s[38:39]
	global_store_dwordx4 v76, v[102:105], s[38:39]
	global_store_dwordx4 v77, v[106:109], s[38:39]
	s_waitcnt vmcnt(0) lgkmcnt(0)
	s_branch .LBB0_1389
.Ldw2_kvqs:
	s_mov_b64 s[10:11], s[86:87]
	s_and_saveexec_b64 s[8:9], s[6:7]
	s_cbranch_execz .LBB0_1126
	s_load_dwordx2 s[10:11], s[10:11], 0x118
	v_mov_b32_e32 v2, 0xc3000
	s_movk_i32 s1, 0xff
	s_waitcnt lgkmcnt(0)
	global_load_dword v2, v2, s[10:11] offset:2560 sc1
	s_add_u32 s10, s10, 0xc3a00
	s_addc_u32 s11, s11, 0
	s_waitcnt vmcnt(0)
	v_cmp_lt_u32_e32 vcc, s1, v2
	s_cbranch_vccnz .LBB0_1125
	s_mov_b32 s22, 1
	v_mov_b32_e32 v2, 0
	s_branch .LBB0_1115
